# attention key-block loop: discarded L2 warm-up loads of the K/V rows three blocks ahead (decode stream keeps HBM saturated); carry LDS reads batched; earlier scan/cprep/epilogue edits
# baseline (speedup 1.0000x reference)
; #define LAS __attribute__((address_space(3)))
; __device__ __forceinline__ void attn_unit(Frame& F, int b, int h, int qt, int kb_lo, int nkb, const bf16* QB, const bf16* KB, const bf16* VT, bf16* OUT, float bias2, f32x4* part, float* tpart) {
;     ...
;     for (int it = 0; it < nkb; ++it) {
;         const int kb = kb_lo + nkb - 1 - it, buf = it & 1; const bool more = (it + 1 < nkb);
;         if (more) { const int k2 = kb - 1;
;             lk[0] = *(const u32x4*)(kg + (size_t)(k2 * 64 + kr0) * BW); lk[1] = *(const u32x4*)(kg + (size_t)(k2 * 64 + kr0 + 32) * BW);
;             lv[0] = *(const u32x4*)(vg + (size_t)vr0 * SEQ + k2 * 64); lv[1] = *(const u32x4*)(vg + (size_t)(vr0 + 64) * SEQ + k2 * 64); }
;         if (kb * 64 < q0 + 15) {
;             const LAS bf16* Kb = Ks + buf * (64 * 136); const LAS bf16* Vb = Vs + buf * (128 * 72);
;             f32x4 s[4];
; #pragma unroll
;             for (int st = 0; st < 4; ++st) { s[st] = (f32x4){bias2, bias2, bias2, bias2};
; #pragma unroll
;                 for (int ks = 0; ks < 4; ++ks) { const bf16x8 af = *(const LAS bf16x8*)(Kb + (16 * st + li) * 136 + 32 * ks + 8 * g); s[st] = __builtin_amdgcn_mfma_f32_16x16x32_bf16(af, qf[ks], s[st], 0, 0, 0); } }
;             float om[4][4], bt[4][4], lt[4], X[4], GT[4];
;             if (kb * 64 + 63 >= q0) {
;                 const int kbase = kb * 64 + 4 * g;
; #pragma unroll
;                 for (int st = 0; st < 4; ++st)
; #pragma unroll
;                     for (int r = 0; r < 4; ++r) { const float e = ex2(s[st][r]); float o = rcpf_(1.0f + e), bb = e * o;
;                         if (kbase + 16 * st + r >= qpos) { o = 1.f; bb = 0.f; }
;                         om[st][r] = o; bt[st][r] = bb; }
;             } else {
; #pragma unroll
;                 for (int st = 0; st < 4; ++st)
; #pragma unroll
;                     for (int r = 0; r < 4; ++r) { const float e = ex2(s[st][r]); const float o = rcpf_(1.0f + e); om[st][r] = o; bt[st][r] = e * o; }
;     ...
;         if (more) { const int nb = buf ^ 1;
;             *(LAS u32x4*)(Ks + nb * (64 * 136) + kr0 * 136 + kc0) = lk[0]; *(LAS u32x4*)(Ks + nb * (64 * 136) + (kr0 + 32) * 136 + kc0) = lk[1];
;             *(LAS u32x4*)(Vs + nb * (128 * 72) + vr0 * 72 + vc0) = lv[0]; *(LAS u32x4*)(Vs + nb * (128 * 72) + (vr0 + 64) * 72 + vc0) = lv[1]; }
;         LDS_WAIT(); __syncthreads();
.LBB0_1059:
	s_or_b64 exec, exec, s[2:3]
	s_xor_b32 s2, s27, 1
	s_mul_i32 s3, s2, 0x4400
	s_add_i32 s3, s3, 0
	s_lshl_b32 s2, s2, 10
	v_add3_u32 v86, s3, v125, v34
	s_add_i32 s3, s3, s2
	s_waitcnt vmcnt(7)
	ds_write_b128 v86, v[56:59]
	s_waitcnt vmcnt(6)
	ds_write_b128 v86, v[60:63] offset:8704
	v_add3_u32 v56, s3, v126, v80
	s_waitcnt vmcnt(5)
	ds_write_b128 v56, v[64:67] offset:34816
	s_waitcnt vmcnt(4)
	ds_write_b128 v56, v[68:71] offset:44032
	s_waitcnt lgkmcnt(0)
	s_add_i32 s24, s24, 1
	s_sub_i32 s26, s26, 64
	s_cmp_eq_u32 s25, s24
	s_waitcnt lgkmcnt(0)
	s_barrier
	s_cbranch_scc1 .LBB0_1102
.LBB0_1060:
	v_add_u32_e32 v58, s26, v119
	s_add_i32 s2, s26, 0xffffff81
	v_add_u32_e32 v56, 0xffffff81, v58
	v_add_u32_e32 v58, 0xffffffa1, v58
	v_ashrrev_i32_e32 v57, 31, v56
	v_ashrrev_i32_e32 v59, 31, v58
	s_ashr_i32 s3, s2, 31
	v_lshlrev_b64 v[56:57], 10, v[56:57]
	v_lshlrev_b64 v[58:59], 10, v[58:59]
	s_lshl_b64 s[2:3], s[2:3], 1
	v_lshl_add_u64 v[56:57], v[78:79], 0, v[56:57]
	v_lshl_add_u64 v[60:61], v[78:79], 0, v[58:59]
	v_lshl_add_u64 v[64:65], v[82:83], 0, s[2:3]
	v_lshl_add_u64 v[68:69], v[84:85], 0, s[2:3]
	s_mov_b32 s4, 0xfffd0000
	s_mov_b32 s5, -1
	v_lshl_add_u64 v[200:201], v[56:57], 0, s[4:5]
	v_lshl_add_u64 v[202:203], v[60:61], 0, s[4:5]
	s_mov_b32 s4, 0xfffffe80
	global_load_dwordx4 v[56:59], v[56:57], off
	s_nop 0
	global_load_dwordx4 v[60:63], v[60:61], off
	v_lshl_add_u64 v[196:197], v[64:65], 0, s[4:5]
	v_lshl_add_u64 v[198:199], v[68:69], 0, s[4:5]
	global_load_dwordx4 v[64:67], v[64:65], off
	s_nop 0
	global_load_dwordx4 v[68:71], v[68:69], off
	global_load_dwordx4 v[204:207], v[200:201], off
	global_load_dwordx4 v[204:207], v[202:203], off
	global_load_dwordx4 v[204:207], v[196:197], off
	global_load_dwordx4 v[204:207], v[198:199], off
	s_sub_i32 s2, s26, 63
	s_and_b32 s27, s24, 1
	v_cmp_lt_i32_e64 s[4:5], s2, v124
	s_and_saveexec_b64 s[2:3], s[4:5]
	s_cbranch_execz .LBB0_1059
	s_mul_i32 s4, s27, 0x4400
	v_add3_u32 v106, v120, s4, v121
	ds_read_b128 v[86:89], v106
	ds_read_b128 v[90:93], v106 offset:64
	v_cmp_ge_i32_e64 s[4:5], s26, v118
	s_waitcnt vmcnt(9) lgkmcnt(1)
	v_mfma_f32_16x16x32_bf16 v[86:89], v[86:89], v[48:51], v[52:55]
	ds_read_b128 v[94:97], v106 offset:4416
	ds_read_b128 v[98:101], v106 offset:8768
	ds_read_b128 v[102:105], v106 offset:13120
	s_waitcnt lgkmcnt(3)
	v_mfma_f32_16x16x32_bf16 v[86:89], v[90:93], v[44:47], v[86:89]
	ds_read_b128 v[90:93], v106 offset:128
	s_waitcnt lgkmcnt(0)
	v_mfma_f32_16x16x32_bf16 v[86:89], v[90:93], v[40:43], v[86:89]
	ds_read_b128 v[90:93], v106 offset:192
	s_waitcnt vmcnt(8) lgkmcnt(0)
	v_mfma_f32_16x16x32_bf16 v[86:89], v[90:93], v[36:39], v[86:89]
	ds_read_b128 v[90:93], v106 offset:4352
	s_nop 6
	v_exp_f32_e32 v116, v86
	v_exp_f32_e32 v117, v87
	v_exp_f32_e32 v150, v88
	s_waitcnt lgkmcnt(0)
	v_mfma_f32_16x16x32_bf16 v[90:93], v[90:93], v[48:51], v[52:55]
	v_exp_f32_e32 v149, v89
	v_add_f32_e32 v157, 1.0, v116
	v_add_f32_e32 v158, 1.0, v117
	v_mfma_f32_16x16x32_bf16 v[90:93], v[94:97], v[44:47], v[90:93]
	ds_read_b128 v[94:97], v106 offset:4480
	v_add_f32_e32 v156, 1.0, v150
	v_add_f32_e32 v155, 1.0, v149
	s_waitcnt lgkmcnt(0)
	v_mfma_f32_16x16x32_bf16 v[90:93], v[94:97], v[40:43], v[90:93]
	ds_read_b128 v[94:97], v106 offset:4544
	s_waitcnt lgkmcnt(0)
	v_mfma_f32_16x16x32_bf16 v[90:93], v[94:97], v[36:39], v[90:93]
	ds_read_b128 v[94:97], v106 offset:8704
	s_nop 6
	v_exp_f32_e32 v114, v90
	s_waitcnt lgkmcnt(0)
	v_mfma_f32_16x16x32_bf16 v[94:97], v[94:97], v[48:51], v[52:55]
	v_exp_f32_e32 v115, v91
	v_exp_f32_e32 v144, v92
	v_exp_f32_e32 v141, v93
	v_mfma_f32_16x16x32_bf16 v[94:97], v[98:101], v[44:47], v[94:97]
	ds_read_b128 v[98:101], v106 offset:8832
	v_add_f32_e32 v153, 1.0, v114
	v_add_f32_e32 v154, 1.0, v115
	s_waitcnt lgkmcnt(0)
	v_mfma_f32_16x16x32_bf16 v[94:97], v[98:101], v[40:43], v[94:97]
	ds_read_b128 v[98:101], v106 offset:8896
	v_add_f32_e32 v152, 1.0, v144
	v_add_f32_e32 v151, 1.0, v141
	s_waitcnt lgkmcnt(0)
	v_mfma_f32_16x16x32_bf16 v[94:97], v[98:101], v[36:39], v[94:97]
	ds_read_b128 v[98:101], v106 offset:13056
	s_nop 6
	v_exp_f32_e32 v112, v94
	s_waitcnt lgkmcnt(0)
	v_mfma_f32_16x16x32_bf16 v[98:101], v[98:101], v[48:51], v[52:55]
	v_exp_f32_e32 v113, v95
	v_exp_f32_e32 v140, v96
	v_exp_f32_e32 v137, v97
	v_mfma_f32_16x16x32_bf16 v[98:101], v[102:105], v[44:47], v[98:101]
	ds_read_b128 v[102:105], v106 offset:13184
	v_add_f32_e32 v147, 1.0, v112
	v_add_f32_e32 v148, 1.0, v113
	s_waitcnt lgkmcnt(0)
	v_mfma_f32_16x16x32_bf16 v[98:101], v[102:105], v[40:43], v[98:101]
	ds_read_b128 v[102:105], v106 offset:13248
	v_add_f32_e32 v146, 1.0, v140
	v_add_f32_e32 v145, 1.0, v137
	s_waitcnt lgkmcnt(0)
	v_mfma_f32_16x16x32_bf16 v[98:101], v[102:105], v[36:39], v[98:101]
	s_nop 7
	v_exp_f32_e32 v110, v98
	v_exp_f32_e32 v111, v99
	v_exp_f32_e32 v136, v100
	v_exp_f32_e32 v135, v101
	v_add_f32_e32 v142, 1.0, v110
	v_add_f32_e32 v143, 1.0, v111
	v_add_f32_e32 v139, 1.0, v136
	v_add_f32_e32 v138, 1.0, v135
	s_and_saveexec_b64 s[6:7], s[4:5]
	s_xor_b64 s[16:17], exec, s[6:7]
	s_cbranch_execz .LBB0_1063
; __device__ __forceinline__ float ex2(float x) { return __builtin_amdgcn_exp2f(x); }
; __device__ __forceinline__ float rcpf_(float x) { return __builtin_amdgcn_rcpf(x); }
; __device__ __forceinline__ void attn_unit(Frame& F, int b, int h, int qt, int kb_lo, int nkb, const bf16* QB, const bf16* KB, const bf16* VT, bf16* OUT, float bias2, f32x4* part, float* tpart) {
;     ...
;             if (kb * 64 + 63 >= q0) {
;                 const int kbase = kb * 64 + 4 * g;
; #pragma unroll
;                 for (int st = 0; st < 4; ++st)
; #pragma unroll
;                     for (int r = 0; r < 4; ++r) { const float e = ex2(s[st][r]); float o = rcpf_(1.0f + e), bb = e * o;
;                         if (kbase + 16 * st + r >= qpos) { o = 1.f; bb = 0.f; }
;                         om[st][r] = o; bt[st][r] = bb; }
	v_rcp_f32_e32 v88, v157
	v_rcp_f32_e32 v89, v158
	v_add_u32_e32 v130, s26, v72
	v_subrev_u32_e32 v91, 62, v130
	v_cmp_lt_i32_e64 s[4:5], v91, v1
	v_rcp_f32_e32 v91, v156
	v_rcp_f32_e32 v92, v155
	v_subrev_u32_e32 v90, 63, v130
	v_pk_mul_f32 v[86:87], v[116:117], v[88:89]
	v_cndmask_b32_e64 v109, 1.0, v89, s[4:5]
	v_subrev_u32_e32 v89, 61, v130
	v_cndmask_b32_e64 v87, 0, v87, s[4:5]
	v_cmp_lt_i32_e64 s[6:7], v90, v76
	v_cmp_lt_i32_e64 s[4:5], v89, v76
	v_subrev_u32_e32 v93, 60, v130
	v_cndmask_b32_e64 v108, 1.0, v88, s[6:7]
	v_mul_f32_e32 v88, v150, v91
	v_cndmask_b32_e64 v134, 1.0, v91, s[4:5]
	v_rcp_f32_e32 v90, v153
	v_rcp_f32_e32 v91, v154
	v_cndmask_b32_e64 v88, 0, v88, s[4:5]
	v_mul_f32_e32 v89, v149, v92
	v_cmp_lt_i32_e64 s[4:5], v93, v76
	v_subrev_u32_e32 v94, 46, v130
	v_rcp_f32_e32 v96, v151
	v_cndmask_b32_e64 v89, 0, v89, s[4:5]
	v_cndmask_b32_e64 v127, 1.0, v92, s[4:5]
	v_cmp_lt_i32_e64 s[4:5], v94, v1
	v_rcp_f32_e32 v94, v152
	v_pk_mul_f32 v[92:93], v[114:115], v[90:91]
	v_subrev_u32_e32 v95, 47, v130
	v_cndmask_b32_e64 v107, 1.0, v91, s[4:5]
	v_subrev_u32_e32 v91, 45, v130
	v_cndmask_b32_e64 v86, 0, v86, s[6:7]
	v_cndmask_b32_e64 v93, 0, v93, s[4:5]
	v_cmp_lt_i32_e64 s[6:7], v95, v76
	v_cmp_lt_i32_e64 s[4:5], v91, v76
	v_subrev_u32_e32 v97, 44, v130
	v_cndmask_b32_e64 v106, 1.0, v90, s[6:7]
	v_mul_f32_e32 v90, v144, v94
	v_cndmask_b32_e64 v133, 1.0, v94, s[4:5]
	v_rcp_f32_e32 v94, v147
	v_rcp_f32_e32 v95, v148
	v_cndmask_b32_e64 v90, 0, v90, s[4:5]
	v_mul_f32_e32 v91, v141, v96
	v_cmp_lt_i32_e64 s[4:5], v97, v76
	v_subrev_u32_e32 v98, 30, v130
	v_subrev_u32_e32 v99, 31, v130
	v_cndmask_b32_e64 v91, 0, v91, s[4:5]
	v_cndmask_b32_e64 v128, 1.0, v96, s[4:5]
	v_cmp_lt_i32_e64 s[4:5], v98, v1
	v_rcp_f32_e32 v98, v146
	v_pk_mul_f32 v[96:97], v[112:113], v[94:95]
	v_cndmask_b32_e64 v105, 1.0, v95, s[4:5]
	v_subrev_u32_e32 v95, 29, v130
	v_cndmask_b32_e64 v92, 0, v92, s[6:7]
	v_cndmask_b32_e64 v97, 0, v97, s[4:5]
	v_cmp_lt_i32_e64 s[6:7], v99, v76
	v_cmp_lt_i32_e64 s[4:5], v95, v76
	v_rcp_f32_e32 v100, v145
	v_cndmask_b32_e64 v104, 1.0, v94, s[6:7]
	v_mul_f32_e32 v94, v140, v98
	v_cndmask_b32_e64 v132, 1.0, v98, s[4:5]
	v_rcp_f32_e32 v98, v142
	v_rcp_f32_e32 v99, v143
	v_subrev_u32_e32 v101, 28, v130
	v_cndmask_b32_e64 v94, 0, v94, s[4:5]
	v_cmp_lt_i32_e64 s[4:5], v101, v76
	v_mul_f32_e32 v95, v137, v100
	v_add_u32_e32 v102, -14, v130
	v_cndmask_b32_e64 v129, 1.0, v100, s[4:5]
	v_pk_mul_f32 v[100:101], v[110:111], v[98:99]
	v_rcp_f32_e32 v110, v139
	v_cndmask_b32_e64 v95, 0, v95, s[4:5]
	v_add_u32_e32 v103, -15, v130
	v_cmp_lt_i32_e64 s[4:5], v102, v1
	v_rcp_f32_e32 v111, v138
	v_cndmask_b32_e64 v96, 0, v96, s[6:7]
	v_cmp_lt_i32_e64 s[6:7], v103, v76
	v_cndmask_b32_e64 v103, 1.0, v99, s[4:5]
	v_add_u32_e32 v99, -13, v130
	v_cndmask_b32_e64 v101, 0, v101, s[4:5]
	v_cmp_lt_i32_e64 s[4:5], v99, v76
	v_cndmask_b32_e64 v102, 1.0, v98, s[6:7]
	v_mul_f32_e32 v98, v136, v110
	v_cndmask_b32_e64 v131, 1.0, v110, s[4:5]
	v_add_u32_e32 v110, -12, v130
	v_cndmask_b32_e64 v98, 0, v98, s[4:5]
	v_mul_f32_e32 v99, v135, v111
	v_cmp_lt_i32_e64 s[4:5], v110, v76
	v_cndmask_b32_e64 v100, 0, v100, s[6:7]
	s_nop 0
	v_cndmask_b32_e64 v99, 0, v99, s[4:5]
	v_cndmask_b32_e64 v130, 1.0, v111, s[4:5]
